# GQA/context attention item rebuilt with key-split waves: a wave owns 64 queries and one 32-key half of each tile (every K / V fragment read from LDS feeds two MFMAs), K/V staged by LDS-DMA, key halves
# speedup vs baseline: 1.1018x; 1.0101x over previous
; DI int get_tid() { int t = threadIdx.x; asm volatile("" : "+v"(t)); return t; }
; template <bool NA, bool TRACK>
; DI void attn_item(char* lds, const bf16_t* P, bf16_t* Y, const bf16_t* vt, int rp, int q_off, int k1_off, int nt1,
;                   int vk1, int k2_off, int nt2, int vk2, int g_off, int y_off, int rlo, const float* rpb) {
;   asm volatile("" : "+v"(q_off), "+v"(g_off), "+v"(y_off));
;   const bf16_t* qp = P + q_off;
;   const bf16_t* kp1 = P + k1_off;
;   const bf16_t* kp2 = P + k2_off;
;   const int tid = get_tid(), lane = tid & 63, w = tid >> 6, r = lane & 31, h = lane >> 5;
;   const int lr = tid >> 3, lc = tid & 7;
;   const int nt = nt1 + nt2;
;   const int woff = lr * 128 + ((lc ^ ((lr >> 1) & 7)) << 4);
;   const int swz = (r >> 1) & 7;
;   float* tab = (float*)(lds + 131072);
;   int rw = 0, r0w = 0, cq = 0, c0 = 0;
;   if (NA) {
;     rw = rp * 4 + (w >> 1);
;     r0w = clampi(rw - 4, 0, 24);
;     cq = (w & 1) * 32 + r;
;     c0 = clampi(cq - 8, 0, 48);
;     for (int e = tid; e < 15 * 128; e += NTHREADS) {
;       const int dr = e >> 7, dc = (e & 127) - 48;
;       tab[e] = (dc >= 0 && dc < 31) ? rpb[dr * 31 + dc] * LOG2E : 0.f;
;     }
;   }
;   bf16x8 qf[4];
; #pragma unroll
;   for (int ks = 0; ks < 4; ++ks) qf[ks] = *(const bf16x8*)(qp + (size_t)(w * 32 + r) * INW + ks * 16 + h * 8);
;   u32x2 gate[2][4];
; #pragma unroll
;   for (int dm = 0; dm < 2; ++dm)
; #pragma unroll
;     for (int g = 0; g < 4; ++g)
;       gate[dm][g] = *(const u32x2*)(P + g_off + (size_t)(w * 32 + r) * INW + dm * 32 + 8 * g + 4 * h);
; #pragma unroll
;   for (int ks = 0; ks < 4; ++ks) asm volatile("" : "+v"(qf[ks]));
; #pragma unroll
;   for (int dm = 0; dm < 2; ++dm)
; #pragma unroll
;     for (int g = 0; g < 4; ++g) asm volatile("" : "+v"(gate[dm][g]));
;   f32x16 o[2];
;   o[0] = zero16(); o[1] = zero16();
;   f32x16 negm;
; #pragma unroll
;   for (int i = 0; i < 16; ++i) negm[i] = 0.f;
;   float l_run = 0.f;
;   constexpr int TPI = 4;
;   const int niter = (nt + TPI - 1) / TPI;
;   u32x4 rk[TPI], rv[TPI];
;     ...
;   ATT_LOAD(0);
;   ATT_WRITE(0, 0);
;   __syncthreads();
.LBB0_109:
	s_lshl_b32 s3, s25, 6
	s_add_i32 s12, s3, 0x700
	s_and_b64 s[8:9], s[4:5], exec
	s_cselect_b32 s26, s12, s3
	s_lshl_b32 s10, s10, 6
	s_and_b64 s[8:9], s[4:5], exec
	s_movk_i32 s8, 0x800
	s_cselect_b32 s8, s8, 0x200
	s_add_i32 s13, s8, s10
	s_add_i32 s8, s3, 0xa00
	s_add_i32 s9, s3, 0x300
	s_and_b64 s[4:5], s[4:5], exec
	v_readlane_b32 s36, v254, 41
	s_cselect_b32 s28, s9, s3
	s_cselect_b32 s3, 8, 7
	v_readlane_b32 s46, v254, 51
	v_readlane_b32 s47, v254, 52
	v_readlane_b32 s48, v254, 53
	v_readlane_b32 s49, v254, 54
	s_cselect_b32 s27, s8, s9
	s_cselect_b32 s4, s49, s47
	s_cselect_b32 s5, s48, s46
	s_lshl_b32 s3, s0, s3
	s_add_i32 s3, s3, s10
	s_mul_hi_i32 s9, s3, 0x1200
	s_mulk_i32 s3, 0x1200
	s_add_u32 s8, s5, s3
	s_mul_i32 s0, s0, 0xb0000
	s_addc_u32 s9, s4, s9
	s_add_i32 s0, s0, s13
	s_mul_i32 s3, s11, 0xb00
	s_mulk_i32 s2, 0xb00
	s_add_i32 s10, s0, 0x5800000
	s_lshl_b32 s0, s11, 10
	s_add_i32 s26, s26, s3
	s_add_i32 s12, s13, s2
	s_add_i32 s27, s27, s3
	s_add_i32 s28, s28, s0
	s_andn2_b64 vcc, exec, s[6:7]
	s_mov_b64 s[2:3], -1
	v_readlane_b32 s37, v254, 42
	v_readlane_b32 s38, v254, 43
	v_readlane_b32 s39, v254, 44
	v_readlane_b32 s40, v254, 45
	v_readlane_b32 s41, v254, 46
	v_readlane_b32 s42, v254, 47
	v_readlane_b32 s43, v254, 48
	v_readlane_b32 s44, v254, 49
	v_readlane_b32 s45, v254, 50
	v_readlane_b32 s50, v254, 55
	v_readlane_b32 s51, v254, 56
	s_cbranch_vccz .LBB0_184
	v_readlane_b32 s4, v255, 10
	v_readlane_b32 s5, v255, 11
	s_ashr_i32 s13, s12, 31
	s_ashr_i32 s11, s10, 31
	s_and_b64 vcc, exec, s[4:5]
	s_cbranch_vccz .LBB0_156
	v_readlane_b32 s44, v254, 49
	v_readlane_b32 s45, v254, 50
	s_mov_b32 s34, s26
	s_ashr_i32 s35, s26, 31
	s_lshl_b64 s[34:35], s[34:35], 1
	s_add_u32 s34, s34, s44
	s_addc_u32 s35, s35, s45
	s_mov_b32 s36, s27
	s_ashr_i32 s37, s27, 31
	s_lshl_b64 s[36:37], s[36:37], 1
	s_add_u32 s36, s36, s44
	s_addc_u32 s37, s37, s45
	s_lshl_b64 s[4:5], s[12:13], 1
	s_add_u32 s4, s4, s44
	s_addc_u32 s5, s5, s45
	s_lshl_b64 s[6:7], s[10:11], 1
	s_add_u32 s6, s6, s44
	s_addc_u32 s7, s7, s45
	s_add_i32 s19, s79, 4
	s_lshr_b32 s19, s19, 2
	s_mov_b32 s18, 0
	s_add_u32 s46, s34, 0x2c000
	s_addc_u32 s47, s35, 0
	v_lshrrev_b32_e32 v0, 6, v251
	s_nop 0
	v_readfirstlane_b32 s38, v0
	s_nop 3
	s_lshl_b32 s30, s38, 10
	s_mul_i32 s39, s38, 0x2400
	s_xor_b32 s40, s38, 1
	s_mul_i32 s40, s40, 0x2400
	s_and_b32 s38, s38, 1
	v_lshrrev_b32_e32 v225, 7, v251
	v_and_b32_e32 v226, 31, v251
	v_lshl_or_b32 v225, v225, 6, v226
	v_bfe_u32 v227, v251, 5, 1
	v_mul_u32_u24_e32 v225, 0x1600, v225
	v_lshl_add_u32 v224, v227, 4, v225
	global_load_dwordx4 v[130:133], v224, s[34:35]
	global_load_dwordx4 v[134:137], v224, s[34:35] offset:32
	global_load_dwordx4 v[138:141], v224, s[34:35] offset:64
	global_load_dwordx4 v[142:145], v224, s[34:35] offset:96
	global_load_dwordx4 v[146:149], v224, s[46:47]
	global_load_dwordx4 v[150:153], v224, s[46:47] offset:32
	global_load_dwordx4 v[154:157], v224, s[46:47] offset:64
	global_load_dwordx4 v[158:161], v224, s[46:47] offset:96
	v_lshrrev_b32_e32 v0, 3, v251
	v_and_b32_e32 v225, 7, v251
	v_bfe_u32 v226, v251, 4, 3
	v_xor_b32_e32 v225, v225, v226
	v_mul_u32_u24_e32 v222, 0x1600, v0
	v_lshl_add_u32 v222, v225, 4, v222
	v_mul_u32_u24_e32 v223, 0x1200, v0
	v_lshl_add_u32 v223, v225, 4, v223
	s_mov_b32 s20, 0
	s_and_b32 s31, s20, 1
	s_lshl_b32 s31, s31, 16
	s_add_u32 s31, s31, s30
	s_lshl_b32 s20, s20, 2
	s_cmp_lt_i32 s20, s79
	s_cselect_b32 s21, 0, s79
	s_cselect_b32 s22, s4, s6
	s_cselect_b32 s23, s5, s7
	s_cselect_b32 s29, s90, 0x800
	s_sub_i32 s20, s20, s21
	s_mul_i32 s21, s20, 0x58000
	s_add_u32 s14, s22, s21
	s_addc_u32 s15, s23, 0
	s_lshl_b32 s20, s20, 6
	s_add_i32 s20, s20, s29
	s_lshl_b32 s20, s20, 1
	s_add_u32 s16, s8, s20
	s_addc_u32 s17, s9, 0
	s_add_u32 m0, s31, 0x0
	s_nop 0
	global_load_lds_dwordx4 v222, s[14:15]
	s_add_u32 m0, s31, 0x2000
	s_nop 0
	global_load_lds_dwordx4 v223, s[16:17]
	s_add_u32 s14, s14, 0x58000
	s_addc_u32 s15, s15, 0
	s_add_u32 s16, s16, 0x80
	s_addc_u32 s17, s17, 0
	s_add_u32 m0, s31, 0x4000
	s_nop 0
	global_load_lds_dwordx4 v222, s[14:15]
	s_add_u32 m0, s31, 0x6000
	s_nop 0
	global_load_lds_dwordx4 v223, s[16:17]
	s_add_u32 s14, s14, 0x58000
	s_addc_u32 s15, s15, 0
	s_add_u32 s16, s16, 0x80
	s_addc_u32 s17, s17, 0
	s_add_u32 m0, s31, 0x8000
	s_nop 0
	global_load_lds_dwordx4 v222, s[14:15]
	s_add_u32 m0, s31, 0xa000
	s_nop 0
	global_load_lds_dwordx4 v223, s[16:17]
	s_add_u32 s14, s14, 0x58000
	s_addc_u32 s15, s15, 0
	s_add_u32 s16, s16, 0x80
	s_addc_u32 s17, s17, 0
	s_add_u32 m0, s31, 0xc000
	s_nop 0
	global_load_lds_dwordx4 v222, s[14:15]
	s_add_u32 m0, s31, 0xe000
	s_nop 0
	global_load_lds_dwordx4 v223, s[16:17]
	v_and_b32_e32 v0, 31, v251
	v_lshlrev_b32_e32 v0, 7, v0
	v_bfe_u32 v225, v251, 1, 3
	v_xor_b32_e32 v225, v225, v227
	v_bfe_u32 v226, v251, 6, 1
	v_lshl_or_b32 v228, v226, 12, v0
	v_lshl_or_b32 v216, v225, 4, v228
	v_xor_b32_e32 v229, 2, v225
	v_lshl_or_b32 v217, v229, 4, v228
	v_xor_b32_e32 v229, 4, v225
	v_lshl_or_b32 v218, v229, 4, v228
	v_xor_b32_e32 v229, 6, v225
	v_lshl_or_b32 v219, v229, 4, v228
	v_lshlrev_b32_e32 v226, 2, v226
	v_xor_b32_e32 v225, v225, v226
	v_lshl_or_b32 v220, v225, 4, v0
	v_xor_b32_e32 v229, 2, v225
	v_lshl_or_b32 v221, v229, 4, v0
	v_mov_b32_e32 v2, 0
	v_mov_b32_e32 v3, 0
	v_mov_b32_e32 v4, 0
	v_mov_b32_e32 v5, 0
	v_mov_b32_e32 v6, 0
	v_mov_b32_e32 v7, 0
	v_mov_b32_e32 v8, 0
	v_mov_b32_e32 v9, 0
	v_mov_b32_e32 v10, 0
	v_mov_b32_e32 v11, 0
	v_mov_b32_e32 v12, 0
	v_mov_b32_e32 v13, 0
	v_mov_b32_e32 v14, 0
	v_mov_b32_e32 v15, 0
	v_mov_b32_e32 v16, 0
	v_mov_b32_e32 v17, 0
	v_mov_b32_e32 v18, 0
	v_mov_b32_e32 v19, 0
	v_mov_b32_e32 v20, 0
	v_mov_b32_e32 v21, 0
	v_mov_b32_e32 v22, 0
	v_mov_b32_e32 v23, 0
	v_mov_b32_e32 v24, 0
	v_mov_b32_e32 v25, 0
	v_mov_b32_e32 v26, 0
	v_mov_b32_e32 v27, 0
	v_mov_b32_e32 v28, 0
	v_mov_b32_e32 v29, 0
	v_mov_b32_e32 v30, 0
	v_mov_b32_e32 v31, 0
	v_mov_b32_e32 v32, 0
	v_mov_b32_e32 v33, 0
	v_mov_b32_e32 v34, 0
	v_mov_b32_e32 v35, 0
	v_mov_b32_e32 v36, 0
	v_mov_b32_e32 v37, 0
	v_mov_b32_e32 v38, 0
	v_mov_b32_e32 v39, 0
	v_mov_b32_e32 v40, 0
	v_mov_b32_e32 v41, 0
	v_mov_b32_e32 v42, 0
	v_mov_b32_e32 v43, 0
	v_mov_b32_e32 v44, 0
	v_mov_b32_e32 v45, 0
	v_mov_b32_e32 v46, 0
	v_mov_b32_e32 v47, 0
	v_mov_b32_e32 v48, 0
	v_mov_b32_e32 v49, 0
	v_mov_b32_e32 v50, 0
	v_mov_b32_e32 v51, 0
	v_mov_b32_e32 v52, 0
	v_mov_b32_e32 v53, 0
	v_mov_b32_e32 v54, 0
	v_mov_b32_e32 v55, 0
	v_mov_b32_e32 v56, 0
	v_mov_b32_e32 v57, 0
	v_mov_b32_e32 v58, 0
	v_mov_b32_e32 v59, 0
	v_mov_b32_e32 v60, 0
	v_mov_b32_e32 v61, 0
	v_mov_b32_e32 v62, 0
	v_mov_b32_e32 v63, 0
	v_mov_b32_e32 v64, 0
	v_mov_b32_e32 v65, 0
	v_mov_b32_e32 v212, 0
	v_mov_b32_e32 v213, 0
	v_mov_b32_e32 v214, 0
	v_mov_b32_e32 v215, 0
	s_waitcnt vmcnt(0)
	s_barrier
; template <bool NA, bool TRACK>
; DI void attn_item(char* lds, const bf16_t* P, bf16_t* Y, const bf16_t* vt, int rp, int q_off, int k1_off, int nt1,
;                   int vk1, int k2_off, int nt2, int vk2, int g_off, int y_off, int rlo, const float* rpb) {
;     ...
;       const bool more = it + 1 < niter;
;       if (more) ATT_LOAD2(it + 1, 0);
;       const char* Kb = lds + hb * 65536;
;       f32x16 sc[2], sn[2];
;     ...
;       ATT_QK(sc, 0);
; #pragma unroll
;       for (int j = 0; j < TPI; ++j) {
;         const char* Vs = Kb + j * 16384 + 8192;
;         if (j + 1 < TPI) ATT_QK(sn, j + 1);
;         float ps = 0.f;
; #pragma unroll
.Ldk_loop:
	ds_read_b128 v[162:165], v216
	ds_read_b128 v[166:169], v217
	ds_read_b128 v[170:173], v218
	ds_read_b128 v[174:177], v219
	ds_read_b128 v[178:181], v220 offset:8192
	ds_read_b128 v[182:185], v220 offset:12288
	ds_read_b128 v[186:189], v221 offset:8192
	ds_read_b128 v[192:195], v221 offset:12288
	s_add_i32 s20, s18, 1
	s_cmp_ge_i32 s20, s19
	s_cbranch_scc1 .Ldk_skip_loop
	s_and_b32 s31, s20, 1
	s_lshl_b32 s31, s31, 16
	s_add_u32 s31, s31, s30
	s_lshl_b32 s20, s20, 2
	s_cmp_lt_i32 s20, s79
	s_cselect_b32 s21, 0, s79
	s_cselect_b32 s22, s4, s6
	s_cselect_b32 s23, s5, s7
	s_cselect_b32 s29, s90, 0x800
	s_sub_i32 s20, s20, s21
	s_mul_i32 s21, s20, 0x58000
	s_add_u32 s14, s22, s21
	s_addc_u32 s15, s23, 0
	s_lshl_b32 s20, s20, 6
	s_add_i32 s20, s20, s29
	s_lshl_b32 s20, s20, 1
	s_add_u32 s16, s8, s20
	s_addc_u32 s17, s9, 0
	s_add_u32 m0, s31, 0x0
	s_nop 0
	global_load_lds_dwordx4 v222, s[14:15]
	s_add_u32 m0, s31, 0x2000
	s_nop 0
	global_load_lds_dwordx4 v223, s[16:17]
	s_add_u32 s14, s14, 0x58000
	s_addc_u32 s15, s15, 0
	s_add_u32 s16, s16, 0x80
	s_addc_u32 s17, s17, 0
	s_add_u32 m0, s31, 0x4000
	s_nop 0
	global_load_lds_dwordx4 v222, s[14:15]
	s_add_u32 m0, s31, 0x6000
	s_nop 0
	global_load_lds_dwordx4 v223, s[16:17]
	s_add_u32 s14, s14, 0x58000
	s_addc_u32 s15, s15, 0
	s_add_u32 s16, s16, 0x80
	s_addc_u32 s17, s17, 0
	s_add_u32 m0, s31, 0x8000
	s_nop 0
	global_load_lds_dwordx4 v222, s[14:15]
	s_add_u32 m0, s31, 0xa000
	s_nop 0
	global_load_lds_dwordx4 v223, s[16:17]
	s_add_u32 s14, s14, 0x58000
	s_addc_u32 s15, s15, 0
	s_add_u32 s16, s16, 0x80
	s_addc_u32 s17, s17, 0
	s_add_u32 m0, s31, 0xc000
	s_nop 0
	global_load_lds_dwordx4 v222, s[14:15]
	s_add_u32 m0, s31, 0xe000
	s_nop 0
	global_load_lds_dwordx4 v223, s[16:17]
.Ldk_skip_loop:
	s_waitcnt lgkmcnt(7)
	v_mfma_f32_32x32x16_bf16 v[66:81], v[162:165], v[130:133], 0
	v_mfma_f32_32x32x16_bf16 v[82:97], v[162:165], v[146:149], 0
	ds_read_b128 v[162:165], v216 offset:16384
	s_waitcnt lgkmcnt(7)
	v_mfma_f32_32x32x16_bf16 v[66:81], v[166:169], v[134:137], v[66:81]
	v_mfma_f32_32x32x16_bf16 v[82:97], v[166:169], v[150:153], v[82:97]
	ds_read_b128 v[166:169], v217 offset:16384
	s_waitcnt lgkmcnt(7)
	v_mfma_f32_32x32x16_bf16 v[66:81], v[170:173], v[138:141], v[66:81]
	v_mfma_f32_32x32x16_bf16 v[82:97], v[170:173], v[154:157], v[82:97]
	ds_read_b128 v[170:173], v218 offset:16384
	s_waitcnt lgkmcnt(7)
	v_mfma_f32_32x32x16_bf16 v[66:81], v[174:177], v[142:145], v[66:81]
	v_mfma_f32_32x32x16_bf16 v[82:97], v[174:177], v[158:161], v[82:97]
	ds_read_b128 v[174:177], v219 offset:16384
	s_nop 7
	s_nop 3
	v_exp_f32_e32 v66, v66
	v_exp_f32_e32 v67, v67
	v_exp_f32_e32 v68, v68
	v_exp_f32_e32 v69, v69
	v_cvt_pk_bf16_f32 v196, v66, v67
	v_add_f32_e32 v212, v212, v66
	v_add_f32_e32 v213, v213, v67
	v_exp_f32_e32 v70, v70
	v_exp_f32_e32 v71, v71
	v_cvt_pk_bf16_f32 v197, v68, v69
	v_add_f32_e32 v212, v212, v68
	v_add_f32_e32 v213, v213, v69
	v_exp_f32_e32 v72, v72
	v_exp_f32_e32 v73, v73
	v_add_f32_e32 v212, v212, v70
	v_add_f32_e32 v213, v213, v71
	v_cvt_pk_bf16_f32 v198, v70, v71
	v_add_f32_e32 v212, v212, v72
	v_add_f32_e32 v213, v213, v73
	v_cvt_pk_bf16_f32 v199, v72, v73
	s_nop 1
	s_waitcnt lgkmcnt(3)
	v_mfma_f32_32x32x16_bf16 v[98:113], v[162:165], v[130:133], 0
	v_exp_f32_e32 v74, v74
	v_exp_f32_e32 v75, v75
	v_exp_f32_e32 v76, v76
	v_mfma_f32_32x32x16_bf16 v[114:129], v[162:165], v[146:149], 0
	ds_read_b128 v[162:165], v216 offset:32768
	v_exp_f32_e32 v77, v77
	v_cvt_pk_bf16_f32 v200, v74, v75
	v_add_f32_e32 v212, v212, v74
	v_add_f32_e32 v213, v213, v75
	v_exp_f32_e32 v78, v78
	s_waitcnt lgkmcnt(3)
	v_mfma_f32_32x32x16_bf16 v[98:113], v[166:169], v[134:137], v[98:113]
	v_exp_f32_e32 v79, v79
	v_cvt_pk_bf16_f32 v201, v76, v77
	v_add_f32_e32 v212, v212, v76
	v_add_f32_e32 v213, v213, v77
	v_exp_f32_e32 v80, v80
	v_mfma_f32_32x32x16_bf16 v[114:129], v[166:169], v[150:153], v[114:129]
	ds_read_b128 v[166:169], v217 offset:32768
	v_exp_f32_e32 v81, v81
	v_add_f32_e32 v212, v212, v78
	v_add_f32_e32 v213, v213, v79
	v_cvt_pk_bf16_f32 v202, v78, v79
	v_add_f32_e32 v212, v212, v80
	v_add_f32_e32 v213, v213, v81
	v_cvt_pk_bf16_f32 v203, v80, v81
	v_mfma_f32_32x32x16_bf16 v[18:33], v[178:181], v[196:199], v[18:33]
	v_exp_f32_e32 v82, v82
	v_exp_f32_e32 v83, v83
	v_exp_f32_e32 v84, v84
	v_mfma_f32_32x32x16_bf16 v[2:17], v[182:185], v[196:199], v[2:17]
	v_exp_f32_e32 v85, v85
	v_cvt_pk_bf16_f32 v204, v82, v83
	v_add_f32_e32 v214, v214, v82
	v_add_f32_e32 v215, v215, v83
	v_exp_f32_e32 v86, v86
	v_mfma_f32_32x32x16_bf16 v[18:33], v[186:189], v[200:203], v[18:33]
	v_exp_f32_e32 v87, v87
	v_cvt_pk_bf16_f32 v205, v84, v85
	v_add_f32_e32 v214, v214, v84
	v_add_f32_e32 v215, v215, v85
	v_exp_f32_e32 v88, v88
	v_mfma_f32_32x32x16_bf16 v[2:17], v[192:195], v[200:203], v[2:17]
	v_exp_f32_e32 v89, v89
	v_add_f32_e32 v214, v214, v86
	v_add_f32_e32 v215, v215, v87
	v_cvt_pk_bf16_f32 v206, v86, v87
	v_add_f32_e32 v214, v214, v88
	v_add_f32_e32 v215, v215, v89
	v_cvt_pk_bf16_f32 v207, v88, v89
	s_waitcnt lgkmcnt(3)
	v_mfma_f32_32x32x16_bf16 v[98:113], v[170:173], v[138:141], v[98:113]
	v_exp_f32_e32 v90, v90
	v_exp_f32_e32 v91, v91
	v_exp_f32_e32 v92, v92
	v_mfma_f32_32x32x16_bf16 v[114:129], v[170:173], v[154:157], v[114:129]
	ds_read_b128 v[170:173], v218 offset:32768
	v_exp_f32_e32 v93, v93
	v_cvt_pk_bf16_f32 v208, v90, v91
	v_add_f32_e32 v214, v214, v90
	v_add_f32_e32 v215, v215, v91
	v_exp_f32_e32 v94, v94
	s_waitcnt lgkmcnt(3)
; DI f32x16 mfma32(bf16x8 a, bf16x8 b, f32x16 c) { return __builtin_amdgcn_mfma_f32_32x32x16_bf16(a, b, c, 0, 0, 0); }
; DI float fast_exp2(float x) { return __builtin_amdgcn_exp2f(x); }
; #define ATT_WRITE2(HALF, H) do { _Pragma("unroll") for (int j_ = 0; j_ < 2; ++j_) { \
;       char* sl_ = lds + (HALF) * 65536 + (2 * (H) + j_) * 16384; \
;       *(u32x4*)(sl_ + woff) = rk[j_]; \
;       *(u32x4*)(sl_ + 8192 + woff) = rv[j_]; } } while (0)
; template <bool NA, bool TRACK>
; DI void attn_item(char* lds, const bf16_t* P, bf16_t* Y, const bf16_t* vt, int rp, int q_off, int k1_off, int nt1,
;                   int vk1, int k2_off, int nt2, int vk2, int g_off, int y_off, int rlo, const float* rpb) {
;     ...
;       for (int j = 0; j < TPI; ++j) {
;         const char* Vs = Kb + j * 16384 + 8192;
;         if (j + 1 < TPI) ATT_QK(sn, j + 1);
;         float ps = 0.f;
; #pragma unroll
;         for (int kt = 0; kt < 2; ++kt) {
;           bf16x8 vf[4];
; #pragma unroll
;           for (int sp = 0; sp < 2; ++sp)
; #pragma unroll
;             for (int dm = 0; dm < 2; ++dm)
;               vf[sp * 2 + dm] = *(const bf16x8*)(Vs + (dm * 32 + r) * 128 + (((4 * kt + 2 * sp + h) ^ swz) << 4));
; #pragma unroll
;           for (int i = 0; i < 16; ++i) {
;             const float pv = fast_exp2(sc[kt][i]);
;             ps += pv;
;             sc[kt][i] = pv;
;           }
; #pragma unroll
;           for (int sp = 0; sp < 2; ++sp) {
;             u32x4 pu;
;             pu[0] = pk2(sc[kt][8 * sp + 0], sc[kt][8 * sp + 1]);
;             pu[1] = pk2(sc[kt][8 * sp + 2], sc[kt][8 * sp + 3]);
;             pu[2] = pk2(sc[kt][8 * sp + 4], sc[kt][8 * sp + 5]);
;             pu[3] = pk2(sc[kt][8 * sp + 6], sc[kt][8 * sp + 7]);
;             const bf16x8 pf = __builtin_bit_cast(bf16x8, pu);
; #pragma unroll
;             for (int dm = 0; dm < 2; ++dm) o[dm] = mfma32(vf[sp * 2 + dm], pf, o[dm]);
;           }
;         }
;         l_run += ps;
;         if (j + 1 < TPI) { sc[0] = sn[0]; sc[1] = sn[1]; }
;         if (j == 1 && more) { ATT_WRITE2(hb ^ 1, 0); ATT_LOAD2(it + 1, 1); }
;       }
	v_mfma_f32_32x32x16_bf16 v[98:113], v[174:177], v[142:145], v[98:113]
	v_exp_f32_e32 v95, v95
	v_cvt_pk_bf16_f32 v209, v92, v93
	v_add_f32_e32 v214, v214, v92
	v_add_f32_e32 v215, v215, v93
	v_exp_f32_e32 v96, v96
	v_mfma_f32_32x32x16_bf16 v[114:129], v[174:177], v[158:161], v[114:129]
	ds_read_b128 v[174:177], v219 offset:32768
	v_exp_f32_e32 v97, v97
	v_add_f32_e32 v214, v214, v94
	v_add_f32_e32 v215, v215, v95
	v_cvt_pk_bf16_f32 v210, v94, v95
	v_add_f32_e32 v214, v214, v96
	v_add_f32_e32 v215, v215, v97
	v_cvt_pk_bf16_f32 v211, v96, v97
	v_mfma_f32_32x32x16_bf16 v[50:65], v[178:181], v[204:207], v[50:65]
	s_nop 1
	v_exp_f32_e32 v98, v98
	v_exp_f32_e32 v99, v99
	v_exp_f32_e32 v100, v100
	v_mfma_f32_32x32x16_bf16 v[34:49], v[182:185], v[204:207], v[34:49]
	ds_read_b128 v[178:181], v220 offset:24576
	ds_read_b128 v[182:185], v220 offset:28672
	v_exp_f32_e32 v101, v101
	v_cvt_pk_bf16_f32 v196, v98, v99
	v_add_f32_e32 v212, v212, v98
	v_add_f32_e32 v213, v213, v99
	v_exp_f32_e32 v102, v102
	v_mfma_f32_32x32x16_bf16 v[50:65], v[186:189], v[208:211], v[50:65]
	v_exp_f32_e32 v103, v103
	v_cvt_pk_bf16_f32 v197, v100, v101
	v_add_f32_e32 v212, v212, v100
	v_add_f32_e32 v213, v213, v101
	v_exp_f32_e32 v104, v104
	v_mfma_f32_32x32x16_bf16 v[34:49], v[192:195], v[208:211], v[34:49]
	ds_read_b128 v[186:189], v221 offset:24576
	ds_read_b128 v[192:195], v221 offset:28672
	v_exp_f32_e32 v105, v105
	v_add_f32_e32 v212, v212, v102
	v_add_f32_e32 v213, v213, v103
	v_cvt_pk_bf16_f32 v198, v102, v103
	v_add_f32_e32 v212, v212, v104
	v_add_f32_e32 v213, v213, v105
	v_cvt_pk_bf16_f32 v199, v104, v105
	s_waitcnt lgkmcnt(7)
	v_mfma_f32_32x32x16_bf16 v[66:81], v[162:165], v[130:133], 0
	v_exp_f32_e32 v106, v106
	v_exp_f32_e32 v107, v107
	v_exp_f32_e32 v108, v108
	v_mfma_f32_32x32x16_bf16 v[82:97], v[162:165], v[146:149], 0
	ds_read_b128 v[162:165], v216 offset:49152
	v_exp_f32_e32 v109, v109
	v_cvt_pk_bf16_f32 v200, v106, v107
	v_add_f32_e32 v212, v212, v106
	v_add_f32_e32 v213, v213, v107
	v_exp_f32_e32 v110, v110
	s_waitcnt lgkmcnt(7)
	v_mfma_f32_32x32x16_bf16 v[66:81], v[166:169], v[134:137], v[66:81]
	v_exp_f32_e32 v111, v111
	v_cvt_pk_bf16_f32 v201, v108, v109
	v_add_f32_e32 v212, v212, v108
	v_add_f32_e32 v213, v213, v109
	v_exp_f32_e32 v112, v112
	v_mfma_f32_32x32x16_bf16 v[82:97], v[166:169], v[150:153], v[82:97]
	ds_read_b128 v[166:169], v217 offset:49152
	v_exp_f32_e32 v113, v113
	v_add_f32_e32 v212, v212, v110
	v_add_f32_e32 v213, v213, v111
	v_cvt_pk_bf16_f32 v202, v110, v111
	v_add_f32_e32 v212, v212, v112
	v_add_f32_e32 v213, v213, v113
	v_cvt_pk_bf16_f32 v203, v112, v113
	s_waitcnt lgkmcnt(5)
	v_mfma_f32_32x32x16_bf16 v[18:33], v[178:181], v[196:199], v[18:33]
	v_exp_f32_e32 v114, v114
	v_exp_f32_e32 v115, v115
	v_exp_f32_e32 v116, v116
	s_waitcnt lgkmcnt(4)
	v_mfma_f32_32x32x16_bf16 v[2:17], v[182:185], v[196:199], v[2:17]
	v_exp_f32_e32 v117, v117
	v_cvt_pk_bf16_f32 v204, v114, v115
	v_add_f32_e32 v214, v214, v114
	v_add_f32_e32 v215, v215, v115
	v_exp_f32_e32 v118, v118
	s_waitcnt lgkmcnt(3)
	v_mfma_f32_32x32x16_bf16 v[18:33], v[186:189], v[200:203], v[18:33]
	v_exp_f32_e32 v119, v119
	v_cvt_pk_bf16_f32 v205, v116, v117
	v_add_f32_e32 v214, v214, v116
	v_add_f32_e32 v215, v215, v117
	v_exp_f32_e32 v120, v120
	s_waitcnt lgkmcnt(2)
	v_mfma_f32_32x32x16_bf16 v[2:17], v[192:195], v[200:203], v[2:17]
	v_exp_f32_e32 v121, v121
	v_add_f32_e32 v214, v214, v118
	v_add_f32_e32 v215, v215, v119
	v_cvt_pk_bf16_f32 v206, v118, v119
	v_add_f32_e32 v214, v214, v120
	v_add_f32_e32 v215, v215, v121
	v_cvt_pk_bf16_f32 v207, v120, v121
	v_mfma_f32_32x32x16_bf16 v[66:81], v[170:173], v[138:141], v[66:81]
	v_exp_f32_e32 v122, v122
	v_exp_f32_e32 v123, v123
	v_exp_f32_e32 v124, v124
	v_mfma_f32_32x32x16_bf16 v[82:97], v[170:173], v[154:157], v[82:97]
	ds_read_b128 v[170:173], v218 offset:49152
	v_exp_f32_e32 v125, v125
	v_cvt_pk_bf16_f32 v208, v122, v123
	v_add_f32_e32 v214, v214, v122
	v_add_f32_e32 v215, v215, v123
	v_exp_f32_e32 v126, v126
	v_mfma_f32_32x32x16_bf16 v[66:81], v[174:177], v[142:145], v[66:81]
	v_exp_f32_e32 v127, v127
	v_cvt_pk_bf16_f32 v209, v124, v125
	v_add_f32_e32 v214, v214, v124
	v_add_f32_e32 v215, v215, v125
	v_exp_f32_e32 v128, v128
	v_mfma_f32_32x32x16_bf16 v[82:97], v[174:177], v[158:161], v[82:97]
	ds_read_b128 v[174:177], v219 offset:49152
	v_exp_f32_e32 v129, v129
	v_add_f32_e32 v214, v214, v126
	v_add_f32_e32 v215, v215, v127
	v_cvt_pk_bf16_f32 v210, v126, v127
	v_add_f32_e32 v214, v214, v128
	v_add_f32_e32 v215, v215, v129
	v_cvt_pk_bf16_f32 v211, v128, v129
	v_mfma_f32_32x32x16_bf16 v[50:65], v[178:181], v[204:207], v[50:65]
	s_nop 1
	v_exp_f32_e32 v66, v66
	v_exp_f32_e32 v67, v67
	v_exp_f32_e32 v68, v68
	v_mfma_f32_32x32x16_bf16 v[34:49], v[182:185], v[204:207], v[34:49]
	ds_read_b128 v[178:181], v220 offset:40960
	ds_read_b128 v[182:185], v220 offset:45056
	v_exp_f32_e32 v69, v69
	v_cvt_pk_bf16_f32 v196, v66, v67
	v_add_f32_e32 v212, v212, v66
	v_add_f32_e32 v213, v213, v67
	v_exp_f32_e32 v70, v70
	v_mfma_f32_32x32x16_bf16 v[50:65], v[186:189], v[208:211], v[50:65]
	v_exp_f32_e32 v71, v71
	v_cvt_pk_bf16_f32 v197, v68, v69
	v_add_f32_e32 v212, v212, v68
	v_add_f32_e32 v213, v213, v69
	v_exp_f32_e32 v72, v72
	v_mfma_f32_32x32x16_bf16 v[34:49], v[192:195], v[208:211], v[34:49]
	ds_read_b128 v[186:189], v221 offset:40960
	ds_read_b128 v[192:195], v221 offset:45056
	v_exp_f32_e32 v73, v73
	v_add_f32_e32 v212, v212, v70
	v_add_f32_e32 v213, v213, v71
	v_cvt_pk_bf16_f32 v198, v70, v71
	v_add_f32_e32 v212, v212, v72
	v_add_f32_e32 v213, v213, v73
	v_cvt_pk_bf16_f32 v199, v72, v73
	s_waitcnt lgkmcnt(7)
; DI f32x16 mfma32(bf16x8 a, bf16x8 b, f32x16 c) { return __builtin_amdgcn_mfma_f32_32x32x16_bf16(a, b, c, 0, 0, 0); }
; DI float fast_exp2(float x) { return __builtin_amdgcn_exp2f(x); }
; #define ATT_WRITE2(HALF, H) do { _Pragma("unroll") for (int j_ = 0; j_ < 2; ++j_) { \
;       char* sl_ = lds + (HALF) * 65536 + (2 * (H) + j_) * 16384; \
;       *(u32x4*)(sl_ + woff) = rk[j_]; \
;       *(u32x4*)(sl_ + 8192 + woff) = rv[j_]; } } while (0)
; template <bool NA, bool TRACK>
; DI void attn_item(char* lds, const bf16_t* P, bf16_t* Y, const bf16_t* vt, int rp, int q_off, int k1_off, int nt1,
;                   int vk1, int k2_off, int nt2, int vk2, int g_off, int y_off, int rlo, const float* rpb) {
;     ...
;       for (int j = 0; j < TPI; ++j) {
;         const char* Vs = Kb + j * 16384 + 8192;
;         if (j + 1 < TPI) ATT_QK(sn, j + 1);
;         float ps = 0.f;
; #pragma unroll
;         for (int kt = 0; kt < 2; ++kt) {
;           bf16x8 vf[4];
; #pragma unroll
;           for (int sp = 0; sp < 2; ++sp)
; #pragma unroll
;             for (int dm = 0; dm < 2; ++dm)
;               vf[sp * 2 + dm] = *(const bf16x8*)(Vs + (dm * 32 + r) * 128 + (((4 * kt + 2 * sp + h) ^ swz) << 4));
; #pragma unroll
;           for (int i = 0; i < 16; ++i) {
;             const float pv = fast_exp2(sc[kt][i]);
;             ps += pv;
;             sc[kt][i] = pv;
;           }
; #pragma unroll
;           for (int sp = 0; sp < 2; ++sp) {
;             u32x4 pu;
;             pu[0] = pk2(sc[kt][8 * sp + 0], sc[kt][8 * sp + 1]);
;             pu[1] = pk2(sc[kt][8 * sp + 2], sc[kt][8 * sp + 3]);
;             pu[2] = pk2(sc[kt][8 * sp + 4], sc[kt][8 * sp + 5]);
;             pu[3] = pk2(sc[kt][8 * sp + 6], sc[kt][8 * sp + 7]);
;             const bf16x8 pf = __builtin_bit_cast(bf16x8, pu);
; #pragma unroll
;             for (int dm = 0; dm < 2; ++dm) o[dm] = mfma32(vf[sp * 2 + dm], pf, o[dm]);
;           }
;         }
;         l_run += ps;
;         if (j + 1 < TPI) { sc[0] = sn[0]; sc[1] = sn[1]; }
;         if (j == 1 && more) { ATT_WRITE2(hb ^ 1, 0); ATT_LOAD2(it + 1, 1); }
;       }
;       if (more) ATT_WRITE2(hb ^ 1, 1);
	v_mfma_f32_32x32x16_bf16 v[98:113], v[162:165], v[130:133], 0
	v_exp_f32_e32 v74, v74
	v_exp_f32_e32 v75, v75
	v_exp_f32_e32 v76, v76
	v_mfma_f32_32x32x16_bf16 v[114:129], v[162:165], v[146:149], 0
	v_exp_f32_e32 v77, v77
	v_cvt_pk_bf16_f32 v200, v74, v75
	v_add_f32_e32 v212, v212, v74
	v_add_f32_e32 v213, v213, v75
	v_exp_f32_e32 v78, v78
	s_waitcnt lgkmcnt(6)
	v_mfma_f32_32x32x16_bf16 v[98:113], v[166:169], v[134:137], v[98:113]
	v_exp_f32_e32 v79, v79
	v_cvt_pk_bf16_f32 v201, v76, v77
	v_add_f32_e32 v212, v212, v76
	v_add_f32_e32 v213, v213, v77
	v_exp_f32_e32 v80, v80
	v_mfma_f32_32x32x16_bf16 v[114:129], v[166:169], v[150:153], v[114:129]
	v_exp_f32_e32 v81, v81
	v_add_f32_e32 v212, v212, v78
	v_add_f32_e32 v213, v213, v79
	v_cvt_pk_bf16_f32 v202, v78, v79
	v_add_f32_e32 v212, v212, v80
	v_add_f32_e32 v213, v213, v81
	v_cvt_pk_bf16_f32 v203, v80, v81
	s_waitcnt lgkmcnt(3)
	v_mfma_f32_32x32x16_bf16 v[18:33], v[178:181], v[196:199], v[18:33]
	v_exp_f32_e32 v82, v82
	v_exp_f32_e32 v83, v83
	v_exp_f32_e32 v84, v84
	s_waitcnt lgkmcnt(2)
	v_mfma_f32_32x32x16_bf16 v[2:17], v[182:185], v[196:199], v[2:17]
	v_exp_f32_e32 v85, v85
	v_cvt_pk_bf16_f32 v204, v82, v83
	v_add_f32_e32 v214, v214, v82
	v_add_f32_e32 v215, v215, v83
	v_exp_f32_e32 v86, v86
	s_waitcnt lgkmcnt(1)
	v_mfma_f32_32x32x16_bf16 v[18:33], v[186:189], v[200:203], v[18:33]
	v_exp_f32_e32 v87, v87
	v_cvt_pk_bf16_f32 v205, v84, v85
	v_add_f32_e32 v214, v214, v84
	v_add_f32_e32 v215, v215, v85
	v_exp_f32_e32 v88, v88
	s_waitcnt lgkmcnt(0)
	v_mfma_f32_32x32x16_bf16 v[2:17], v[192:195], v[200:203], v[2:17]
	v_exp_f32_e32 v89, v89
	v_add_f32_e32 v214, v214, v86
	v_add_f32_e32 v215, v215, v87
	v_cvt_pk_bf16_f32 v206, v86, v87
	v_add_f32_e32 v214, v214, v88
	v_add_f32_e32 v215, v215, v89
	v_cvt_pk_bf16_f32 v207, v88, v89
	v_mfma_f32_32x32x16_bf16 v[98:113], v[170:173], v[138:141], v[98:113]
	v_exp_f32_e32 v90, v90
	v_exp_f32_e32 v91, v91
	v_exp_f32_e32 v92, v92
	v_mfma_f32_32x32x16_bf16 v[114:129], v[170:173], v[154:157], v[114:129]
	v_exp_f32_e32 v93, v93
	v_cvt_pk_bf16_f32 v208, v90, v91
	v_add_f32_e32 v214, v214, v90
	v_add_f32_e32 v215, v215, v91
	v_exp_f32_e32 v94, v94
	v_mfma_f32_32x32x16_bf16 v[98:113], v[174:177], v[142:145], v[98:113]
	v_exp_f32_e32 v95, v95
	v_cvt_pk_bf16_f32 v209, v92, v93
	v_add_f32_e32 v214, v214, v92
	v_add_f32_e32 v215, v215, v93
	v_exp_f32_e32 v96, v96
	v_mfma_f32_32x32x16_bf16 v[114:129], v[174:177], v[158:161], v[114:129]
	v_exp_f32_e32 v97, v97
	v_add_f32_e32 v214, v214, v94
	v_add_f32_e32 v215, v215, v95
	v_cvt_pk_bf16_f32 v210, v94, v95
	v_add_f32_e32 v214, v214, v96
	v_add_f32_e32 v215, v215, v97
	v_cvt_pk_bf16_f32 v211, v96, v97
	v_mfma_f32_32x32x16_bf16 v[50:65], v[178:181], v[204:207], v[50:65]
	s_nop 1
	v_exp_f32_e32 v98, v98
	v_exp_f32_e32 v99, v99
	v_exp_f32_e32 v100, v100
	v_mfma_f32_32x32x16_bf16 v[34:49], v[182:185], v[204:207], v[34:49]
	ds_read_b128 v[178:181], v220 offset:57344
	ds_read_b128 v[182:185], v220 offset:61440
	v_exp_f32_e32 v101, v101
	v_cvt_pk_bf16_f32 v196, v98, v99
	v_add_f32_e32 v212, v212, v98
	v_add_f32_e32 v213, v213, v99
	v_exp_f32_e32 v102, v102
	v_mfma_f32_32x32x16_bf16 v[50:65], v[186:189], v[208:211], v[50:65]
	v_exp_f32_e32 v103, v103
	v_cvt_pk_bf16_f32 v197, v100, v101
	v_add_f32_e32 v212, v212, v100
	v_add_f32_e32 v213, v213, v101
	v_exp_f32_e32 v104, v104
	v_mfma_f32_32x32x16_bf16 v[34:49], v[192:195], v[208:211], v[34:49]
	ds_read_b128 v[186:189], v221 offset:57344
	ds_read_b128 v[192:195], v221 offset:61440
	v_exp_f32_e32 v105, v105
	v_add_f32_e32 v212, v212, v102
	v_add_f32_e32 v213, v213, v103
	v_cvt_pk_bf16_f32 v198, v102, v103
	v_add_f32_e32 v212, v212, v104
	v_add_f32_e32 v213, v213, v105
	v_cvt_pk_bf16_f32 v199, v104, v105
	v_exp_f32_e32 v106, v106
	v_exp_f32_e32 v107, v107
	v_exp_f32_e32 v108, v108
	s_waitcnt lgkmcnt(3)
	v_mfma_f32_32x32x16_bf16 v[18:33], v[178:181], v[196:199], v[18:33]
	v_exp_f32_e32 v109, v109
	v_cvt_pk_bf16_f32 v200, v106, v107
	v_add_f32_e32 v212, v212, v106
	v_add_f32_e32 v213, v213, v107
	v_exp_f32_e32 v110, v110
	s_waitcnt lgkmcnt(2)
	v_mfma_f32_32x32x16_bf16 v[2:17], v[182:185], v[196:199], v[2:17]
	v_exp_f32_e32 v111, v111
	v_cvt_pk_bf16_f32 v201, v108, v109
	v_add_f32_e32 v212, v212, v108
	v_add_f32_e32 v213, v213, v109
	v_exp_f32_e32 v112, v112
	v_exp_f32_e32 v113, v113
	v_add_f32_e32 v212, v212, v110
	v_add_f32_e32 v213, v213, v111
	v_cvt_pk_bf16_f32 v202, v110, v111
	v_add_f32_e32 v212, v212, v112
	v_add_f32_e32 v213, v213, v113
	v_cvt_pk_bf16_f32 v203, v112, v113
	v_exp_f32_e32 v114, v114
	v_exp_f32_e32 v115, v115
	v_exp_f32_e32 v116, v116
	s_waitcnt lgkmcnt(1)
	v_mfma_f32_32x32x16_bf16 v[18:33], v[186:189], v[200:203], v[18:33]
	v_exp_f32_e32 v117, v117
	v_cvt_pk_bf16_f32 v204, v114, v115
	v_add_f32_e32 v214, v214, v114
	v_add_f32_e32 v215, v215, v115
	v_exp_f32_e32 v118, v118
	s_waitcnt lgkmcnt(0)
	v_mfma_f32_32x32x16_bf16 v[2:17], v[192:195], v[200:203], v[2:17]
	v_exp_f32_e32 v119, v119
	v_cvt_pk_bf16_f32 v205, v116, v117
	v_add_f32_e32 v214, v214, v116
	v_add_f32_e32 v215, v215, v117
	v_exp_f32_e32 v120, v120
	v_exp_f32_e32 v121, v121
	v_add_f32_e32 v214, v214, v118
	v_add_f32_e32 v215, v215, v119
	v_cvt_pk_bf16_f32 v206, v118, v119
	v_add_f32_e32 v214, v214, v120
	v_add_f32_e32 v215, v215, v121
	v_cvt_pk_bf16_f32 v207, v120, v121
	v_exp_f32_e32 v122, v122
	v_exp_f32_e32 v123, v123
	v_exp_f32_e32 v124, v124
	v_mfma_f32_32x32x16_bf16 v[50:65], v[178:181], v[204:207], v[50:65]
	v_exp_f32_e32 v125, v125
	v_cvt_pk_bf16_f32 v208, v122, v123
	v_add_f32_e32 v214, v214, v122
	v_add_f32_e32 v215, v215, v123
	v_exp_f32_e32 v126, v126
	v_mfma_f32_32x32x16_bf16 v[34:49], v[182:185], v[204:207], v[34:49]
	v_exp_f32_e32 v127, v127
	v_cvt_pk_bf16_f32 v209, v124, v125
	v_add_f32_e32 v214, v214, v124
	v_add_f32_e32 v215, v215, v125
	v_exp_f32_e32 v128, v128
	v_exp_f32_e32 v129, v129
	v_add_f32_e32 v214, v214, v126
	v_add_f32_e32 v215, v215, v127
	v_cvt_pk_bf16_f32 v210, v126, v127
	v_add_f32_e32 v214, v214, v128
	v_add_f32_e32 v215, v215, v129
	v_cvt_pk_bf16_f32 v211, v128, v129
	s_nop 1
	v_mfma_f32_32x32x16_bf16 v[50:65], v[186:189], v[208:211], v[50:65]
	v_mfma_f32_32x32x16_bf16 v[34:49], v[192:195], v[208:211], v[34:49]
	s_waitcnt vmcnt(0)
	s_waitcnt lgkmcnt(0)
	s_barrier
; template <bool NA, bool TRACK>
; DI void attn_item(char* lds, const bf16_t* P, bf16_t* Y, const bf16_t* vt, int rp, int q_off, int k1_off, int nt1,
;                   int vk1, int k2_off, int nt2, int vk2, int g_off, int y_off, int rlo, const float* rpb) {
;     ...
;   u32x2 gate[2][4];
; #pragma unroll
;   for (int dm = 0; dm < 2; ++dm)
; #pragma unroll
;     for (int g = 0; g < 4; ++g)
;       gate[dm][g] = *(const u32x2*)(P + g_off + (size_t)(w * 32 + r) * INW + dm * 32 + 8 * g + 4 * h);
;     ...
;     __syncthreads();
;   }
;     ...
;   const float lt = l_run + __shfl_xor(l_run, 32);
	v_xor_b32_e32 v216, 0x10000, v216
	v_xor_b32_e32 v217, 0x10000, v217
	v_xor_b32_e32 v218, 0x10000, v218
	v_xor_b32_e32 v219, 0x10000, v219
	v_xor_b32_e32 v220, 0x10000, v220
	v_xor_b32_e32 v221, 0x10000, v221
	s_add_i32 s18, s18, 1
	s_cmp_lt_i32 s18, s19
	s_cbranch_scc1 .Ldk_loop
	v_bfe_u32 v147, v251, 5, 1
	v_ashrrev_i32_e32 v0, 1, v251
	s_movk_i32 s0, 0xffe0
	v_bfi_b32 v146, s0, v0, v251
	v_lshlrev_b32_e32 v138, 3, v147
	v_mov_b32_e32 v150, s28
	v_mul_u32_u24_e32 v0, 0x1600, v146
	v_lshl_add_u32 v225, v147, 3, v0
	global_load_dwordx2 v[148:149], v225, s[36:37]
	global_load_dwordx2 v[144:145], v225, s[36:37] offset:16
	global_load_dwordx2 v[142:143], v225, s[36:37] offset:32
	global_load_dwordx2 v[140:141], v225, s[36:37] offset:48
	global_load_dwordx2 v[136:137], v225, s[36:37] offset:64
	global_load_dwordx2 v[134:135], v225, s[36:37] offset:80
	global_load_dwordx2 v[132:133], v225, s[36:37] offset:96
	global_load_dwordx2 v[130:131], v225, s[36:37] offset:112
	v_lshlrev_b32_e32 v226, 4, v240
	v_add_u32_e32 v228, s39, v226
	v_add_u32_e32 v229, s40, v226
	v_add_f32_e32 v212, v212, v213
	v_add_f32_e32 v214, v214, v215
	s_cmp_eq_u32 s38, 0
	s_cbranch_scc0 .Ldk_x1
	ds_write_b128 v228, v[34:37]
	ds_write_b128 v228, v[38:41] offset:1024
	ds_write_b128 v228, v[42:45] offset:2048
	ds_write_b128 v228, v[46:49] offset:3072
	ds_write_b128 v228, v[50:53] offset:4096
	ds_write_b128 v228, v[54:57] offset:5120
	ds_write_b128 v228, v[58:61] offset:6144
	ds_write_b128 v228, v[62:65] offset:7168
	ds_write_b32 v228, v214 offset:8192
	s_branch .Ldk_x2
.Ldk_x1:
	ds_write_b128 v228, v[2:5]
	ds_write_b128 v228, v[6:9] offset:1024
	ds_write_b128 v228, v[10:13] offset:2048
	ds_write_b128 v228, v[14:17] offset:3072
	ds_write_b128 v228, v[18:21] offset:4096
	ds_write_b128 v228, v[22:25] offset:5120
	ds_write_b128 v228, v[26:29] offset:6144
	ds_write_b128 v228, v[30:33] offset:7168
	ds_write_b32 v228, v212 offset:8192
.Ldk_x2:
	s_waitcnt lgkmcnt(0)
	s_barrier
	ds_read_b128 v[66:69], v229
	ds_read_b128 v[70:73], v229 offset:1024
	ds_read_b128 v[74:77], v229 offset:2048
	ds_read_b128 v[78:81], v229 offset:3072
	ds_read_b128 v[82:85], v229 offset:4096
	ds_read_b128 v[86:89], v229 offset:5120
	ds_read_b128 v[90:93], v229 offset:6144
	ds_read_b128 v[94:97], v229 offset:7168
	ds_read_b32 v98, v229 offset:8192
	s_waitcnt lgkmcnt(0)
	s_barrier
	s_cmp_eq_u32 s38, 0
	s_cbranch_scc0 .Ldk_y1
	v_add_f32_e32 v2, v2, v66
	v_add_f32_e32 v3, v3, v67
	v_add_f32_e32 v4, v4, v68
	v_add_f32_e32 v5, v5, v69
	v_add_f32_e32 v6, v6, v70
	v_add_f32_e32 v7, v7, v71
	v_add_f32_e32 v8, v8, v72
	v_add_f32_e32 v9, v9, v73
	v_add_f32_e32 v10, v10, v74
	v_add_f32_e32 v11, v11, v75
	v_add_f32_e32 v12, v12, v76
	v_add_f32_e32 v13, v13, v77
	v_add_f32_e32 v14, v14, v78
	v_add_f32_e32 v15, v15, v79
	v_add_f32_e32 v16, v16, v80
	v_add_f32_e32 v17, v17, v81
	v_add_f32_e32 v18, v18, v82
	v_add_f32_e32 v19, v19, v83
	v_add_f32_e32 v20, v20, v84
	v_add_f32_e32 v21, v21, v85
	v_add_f32_e32 v22, v22, v86
	v_add_f32_e32 v23, v23, v87
	v_add_f32_e32 v24, v24, v88
	v_add_f32_e32 v25, v25, v89
	v_add_f32_e32 v26, v26, v90
	v_add_f32_e32 v27, v27, v91
	v_add_f32_e32 v28, v28, v92
	v_add_f32_e32 v29, v29, v93
	v_add_f32_e32 v30, v30, v94
	v_add_f32_e32 v31, v31, v95
	v_add_f32_e32 v32, v32, v96
	v_add_f32_e32 v33, v33, v97
	v_add_f32_e32 v160, v212, v98
	s_branch .Ldk_y2
.Ldk_y1:
	v_add_f32_e32 v2, v34, v66
	v_add_f32_e32 v3, v35, v67
	v_add_f32_e32 v4, v36, v68
	v_add_f32_e32 v5, v37, v69
	v_add_f32_e32 v6, v38, v70
	v_add_f32_e32 v7, v39, v71
	v_add_f32_e32 v8, v40, v72
	v_add_f32_e32 v9, v41, v73
	v_add_f32_e32 v10, v42, v74
	v_add_f32_e32 v11, v43, v75
	v_add_f32_e32 v12, v44, v76
	v_add_f32_e32 v13, v45, v77
	v_add_f32_e32 v14, v46, v78
	v_add_f32_e32 v15, v47, v79
	v_add_f32_e32 v16, v48, v80
	v_add_f32_e32 v17, v49, v81
	v_add_f32_e32 v18, v50, v82
	v_add_f32_e32 v19, v51, v83
	v_add_f32_e32 v20, v52, v84
	v_add_f32_e32 v21, v53, v85
	v_add_f32_e32 v22, v54, v86
	v_add_f32_e32 v23, v55, v87
	v_add_f32_e32 v24, v56, v88
	v_add_f32_e32 v25, v57, v89
	v_add_f32_e32 v26, v58, v90
	v_add_f32_e32 v27, v59, v91
	v_add_f32_e32 v28, v60, v92
	v_add_f32_e32 v29, v61, v93
	v_add_f32_e32 v30, v62, v94
	v_add_f32_e32 v31, v63, v95
	v_add_f32_e32 v32, v64, v96
	v_add_f32_e32 v33, v65, v97
	v_add_f32_e32 v160, v214, v98
; DI float bflo(unsigned u) { return __uint_as_float(u << 16); }
; DI float bfhi(unsigned u) { return __uint_as_float(u & 0xffff0000u); }
; template <bool NA, bool TRACK>
; DI void attn_item(char* lds, const bf16_t* P, bf16_t* Y, const bf16_t* vt, int rp, int q_off, int k1_off, int nt1,
;                   int vk1, int k2_off, int nt2, int vk2, int g_off, int y_off, int rlo, const float* rpb) {
;     ...
;   const float lt = l_run + __shfl_xor(l_run, 32);
;   const float inv = 1.f / lt;
;   int row = w * 32 + r;
;   asm volatile("" : "+v"(row));
;   bf16_t* yp = Y + y_off;
; #pragma unroll
;   for (int dm = 0; dm < 2; ++dm) {
;     u32x2 ov[4];
; #pragma unroll
;     for (int g = 0; g < 4; ++g) {
;       const u32x2 gv = gate[dm][g];
;       ov[g][0] = pk2(o[dm][4 * g + 0] * inv * bflo(gv[0]), o[dm][4 * g + 1] * inv * bfhi(gv[0]));
;       ov[g][1] = pk2(o[dm][4 * g + 2] * inv * bflo(gv[1]), o[dm][4 * g + 3] * inv * bfhi(gv[1]));
;     }
; #pragma unroll
;     for (int a = 0; a < 2; ++a) {
;       const int ga = 2 * a, gb = 2 * a + 1;
;       const unsigned s0 = h ? ov[ga][0] : ov[gb][0], s1 = h ? ov[ga][1] : ov[gb][1];
;       const unsigned r0 = (unsigned)__shfl_xor((int)s0, 32), r1 = (unsigned)__shfl_xor((int)s1, 32);
;       u32x4 wv;
;       wv[0] = h ? r0 : ov[ga][0];
;       wv[1] = h ? r1 : ov[ga][1];
;       wv[2] = h ? ov[gb][0] : r0;
;       wv[3] = h ? ov[gb][1] : r1;
;       *(u32x4*)(yp + (size_t)row * DM + dm * 32 + 8 * (ga + h)) = wv;
;     }
;   }
.Ldk_y2:
	s_waitcnt vmcnt(0)
	ds_bpermute_b32 v0, v190, v160
	v_readlane_b32 s36, v254, 41
	v_ashrrev_i32_e32 v151, 31, v150
	v_readlane_b32 s50, v254, 55
	s_waitcnt lgkmcnt(0)
	v_add_f32_e32 v0, v160, v0
	v_div_scale_f32 v34, s[2:3], v0, v0, 1.0
	v_rcp_f32_e32 v35, v34
	v_readlane_b32 s51, v254, 56
	v_readlane_b32 s37, v254, 42
	v_readlane_b32 s38, v254, 43
	v_fma_f32 v36, -v34, v35, 1.0
	v_fmac_f32_e32 v35, v36, v35
	v_div_scale_f32 v36, vcc, 1.0, v0, 1.0
	v_mul_f32_e32 v37, v36, v35
	v_fma_f32 v38, -v34, v37, v36
	v_fmac_f32_e32 v37, v38, v35
	v_fma_f32 v34, -v34, v37, v36
	v_div_fmas_f32 v34, v34, v35, v37
	v_cmp_eq_u32_e32 vcc, 0, v147
	v_ashrrev_i32_e32 v147, 31, v146
	v_div_fixup_f32 v34, v34, v0, 1.0
	v_lshl_add_u64 v[36:37], v[150:151], 1, s[50:51]
	v_lshlrev_b64 v[38:39], 11, v[146:147]
	v_lshl_add_u64 v[36:37], v[36:37], 0, v[38:39]
	v_pk_mul_f32 v[18:19], v[18:19], v[34:35] op_sel_hi:[1,0]
	v_lshlrev_b32_e32 v38, 16, v148
	v_and_b32_e32 v39, 0xffff0000, v148
	v_pk_mul_f32 v[18:19], v[18:19], v[38:39]
	v_readlane_b32 s39, v254, 44
	v_cvt_pk_bf16_f32 v0, v18, v19
	v_pk_mul_f32 v[18:19], v[20:21], v[34:35] op_sel_hi:[1,0]
	v_lshlrev_b32_e32 v20, 16, v149
	v_and_b32_e32 v21, 0xffff0000, v149
	v_pk_mul_f32 v[18:19], v[18:19], v[20:21]
	v_lshlrev_b32_e32 v20, 16, v144
	v_cvt_pk_bf16_f32 v35, v18, v19
	v_pk_mul_f32 v[18:19], v[22:23], v[34:35] op_sel_hi:[1,0]
	v_and_b32_e32 v21, 0xffff0000, v144
	v_pk_mul_f32 v[18:19], v[18:19], v[20:21]
	v_lshlrev_b32_e32 v20, 16, v145
	v_cvt_pk_bf16_f32 v22, v18, v19
	v_pk_mul_f32 v[18:19], v[24:25], v[34:35] op_sel_hi:[1,0]
	v_and_b32_e32 v21, 0xffff0000, v145
	v_pk_mul_f32 v[18:19], v[18:19], v[20:21]
	v_lshlrev_b32_e32 v20, 16, v142
	v_cvt_pk_bf16_f32 v23, v18, v19
	v_pk_mul_f32 v[18:19], v[26:27], v[34:35] op_sel_hi:[1,0]
	v_and_b32_e32 v21, 0xffff0000, v142
	v_pk_mul_f32 v[18:19], v[18:19], v[20:21]
	v_lshlrev_b32_e32 v20, 16, v143
	v_cvt_pk_bf16_f32 v24, v18, v19
	v_pk_mul_f32 v[18:19], v[28:29], v[34:35] op_sel_hi:[1,0]
	v_and_b32_e32 v21, 0xffff0000, v143
	v_pk_mul_f32 v[18:19], v[18:19], v[20:21]
	v_lshlrev_b32_e32 v20, 16, v140
	v_cvt_pk_bf16_f32 v25, v18, v19
	v_pk_mul_f32 v[18:19], v[30:31], v[34:35] op_sel_hi:[1,0]
	v_and_b32_e32 v21, 0xffff0000, v140
	v_pk_mul_f32 v[18:19], v[18:19], v[20:21]
	v_lshlrev_b32_e32 v20, 16, v141
	v_cvt_pk_bf16_f32 v26, v18, v19
	v_pk_mul_f32 v[18:19], v[32:33], v[34:35] op_sel_hi:[1,0]
	v_and_b32_e32 v21, 0xffff0000, v141
	v_pk_mul_f32 v[18:19], v[18:19], v[20:21]
	v_pk_mul_f32 v[2:3], v[2:3], v[34:35] op_sel_hi:[1,0]
	v_cvt_pk_bf16_f32 v27, v18, v19
	v_cndmask_b32_e32 v18, v0, v22, vcc
	v_cndmask_b32_e32 v19, v35, v23, vcc
	ds_bpermute_b32 v20, v190, v18
	ds_bpermute_b32 v21, v190, v19
	v_readlane_b32 s40, v254, 45
	v_readlane_b32 s41, v254, 46
	v_readlane_b32 s42, v254, 47
	s_waitcnt lgkmcnt(1)
	v_cndmask_b32_e32 v18, v20, v0, vcc
	v_lshlrev_b32_e32 v0, 1, v138
	s_waitcnt lgkmcnt(0)
	v_cndmask_b32_e32 v19, v21, v35, vcc
	v_cndmask_b32_e32 v20, v22, v20, vcc
	v_cndmask_b32_e32 v21, v23, v21, vcc
	v_lshl_add_u64 v[22:23], v[36:37], 0, v[0:1]
	global_store_dwordx4 v[22:23], v[18:21], off
	v_cndmask_b32_e32 v0, v24, v26, vcc
	ds_bpermute_b32 v0, v190, v0
	v_cndmask_b32_e32 v18, v25, v27, vcc
	ds_bpermute_b32 v21, v190, v18
	v_readlane_b32 s43, v254, 48
	v_readlane_b32 s44, v254, 49
	s_waitcnt lgkmcnt(1)
	v_cndmask_b32_e32 v18, v0, v24, vcc
	v_cndmask_b32_e32 v20, v26, v0, vcc
	s_waitcnt lgkmcnt(0)
	v_cndmask_b32_e32 v19, v21, v25, vcc
	v_cndmask_b32_e32 v21, v27, v21, vcc
	global_store_dwordx4 v[22:23], v[18:21], off offset:32
	v_readlane_b32 s45, v254, 50
	v_readlane_b32 s46, v254, 51
	v_lshlrev_b32_e32 v18, 16, v136
	v_and_b32_e32 v19, 0xffff0000, v136
	v_pk_mul_f32 v[2:3], v[2:3], v[18:19]
	v_readlane_b32 s47, v254, 52
	v_cvt_pk_bf16_f32 v0, v2, v3
	v_pk_mul_f32 v[2:3], v[4:5], v[34:35] op_sel_hi:[1,0]
	v_lshlrev_b32_e32 v4, 16, v137
	v_and_b32_e32 v5, 0xffff0000, v137
	v_pk_mul_f32 v[2:3], v[2:3], v[4:5]
	v_lshlrev_b32_e32 v4, 16, v134
	v_cvt_pk_bf16_f32 v18, v2, v3
	v_pk_mul_f32 v[2:3], v[6:7], v[34:35] op_sel_hi:[1,0]
	v_and_b32_e32 v5, 0xffff0000, v134
	v_pk_mul_f32 v[2:3], v[2:3], v[4:5]
	v_lshlrev_b32_e32 v4, 16, v135
	v_cvt_pk_bf16_f32 v6, v2, v3
	v_pk_mul_f32 v[2:3], v[8:9], v[34:35] op_sel_hi:[1,0]
	v_and_b32_e32 v5, 0xffff0000, v135
	v_pk_mul_f32 v[2:3], v[2:3], v[4:5]
	v_lshlrev_b32_e32 v4, 16, v132
	v_cvt_pk_bf16_f32 v7, v2, v3
	v_pk_mul_f32 v[2:3], v[10:11], v[34:35] op_sel_hi:[1,0]
	v_and_b32_e32 v5, 0xffff0000, v132
	v_pk_mul_f32 v[2:3], v[2:3], v[4:5]
	v_lshlrev_b32_e32 v4, 16, v133
	v_cvt_pk_bf16_f32 v8, v2, v3
	v_pk_mul_f32 v[2:3], v[12:13], v[34:35] op_sel_hi:[1,0]
	v_and_b32_e32 v5, 0xffff0000, v133
	v_pk_mul_f32 v[2:3], v[2:3], v[4:5]
	v_lshlrev_b32_e32 v4, 16, v130
	v_cvt_pk_bf16_f32 v9, v2, v3
	v_pk_mul_f32 v[2:3], v[14:15], v[34:35] op_sel_hi:[1,0]
	v_and_b32_e32 v5, 0xffff0000, v130
	v_pk_mul_f32 v[2:3], v[2:3], v[4:5]
	v_lshlrev_b32_e32 v4, 16, v131
	v_cvt_pk_bf16_f32 v10, v2, v3
	v_pk_mul_f32 v[2:3], v[16:17], v[34:35] op_sel_hi:[1,0]
	v_and_b32_e32 v5, 0xffff0000, v131
	v_pk_mul_f32 v[2:3], v[2:3], v[4:5]
	v_readlane_b32 s48, v254, 53
	v_cvt_pk_bf16_f32 v11, v2, v3
	v_cndmask_b32_e32 v2, v0, v6, vcc
	v_cndmask_b32_e32 v3, v18, v7, vcc
	ds_bpermute_b32 v4, v190, v2
	ds_bpermute_b32 v5, v190, v3
	v_readlane_b32 s49, v254, 54
	s_mov_b64 s[2:3], 0
	s_waitcnt lgkmcnt(1)
	v_cndmask_b32_e32 v2, v4, v0, vcc
	s_waitcnt lgkmcnt(0)
	v_cndmask_b32_e32 v3, v5, v18, vcc
	v_cndmask_b32_e32 v4, v6, v4, vcc
	v_cndmask_b32_e32 v5, v7, v5, vcc
	global_store_dwordx4 v[22:23], v[2:5], off offset:64
	v_cndmask_b32_e32 v0, v8, v10, vcc
	ds_bpermute_b32 v0, v190, v0
	v_cndmask_b32_e32 v2, v9, v11, vcc
	ds_bpermute_b32 v5, v190, v2
	s_waitcnt lgkmcnt(1)
	v_cndmask_b32_e32 v2, v0, v8, vcc
	v_cndmask_b32_e32 v4, v10, v0, vcc
	s_waitcnt lgkmcnt(0)
	v_cndmask_b32_e32 v3, v5, v9, vcc
	v_cndmask_b32_e32 v5, v11, v5, vcc
	global_store_dwordx4 v[22:23], v[2:5], off offset:96
